# speedup vs baseline: 1.0017x; 1.0017x over previous
.LBB0_571:
	v_lshl_add_u64 v[52:53], v[52:53], 1, s[52:53]
	s_mov_b32 s69, s59
	v_lshl_add_u64 v[50:51], v[50:51], 1, s[54:55]
	v_add_f32_e32 v241, v16, v32
	v_lshl_add_u64 v[32:33], v[52:53], 0, s[68:69]
	s_add_i32 m0, s14, 0xf000
	v_mov_b32_e32 v1, v0
	global_load_lds_dwordx4 v[32:33], off
	v_lshl_add_u64 v[32:33], v[50:51], 0, s[68:69]
	s_add_i32 m0, s14, 0x12000
	v_mov_b32_e32 v2, v0
	global_load_lds_dwordx4 v[32:33], off
	v_mov_b32_e32 v3, v0
	v_mov_b32_e32 v4, v0
	v_mov_b32_e32 v5, v0
	v_mov_b32_e32 v6, v0
	v_mov_b32_e32 v7, v0
	v_mov_b32_e32 v8, v0
	v_mov_b32_e32 v9, v0
	v_mov_b32_e32 v10, v0
	v_mov_b32_e32 v11, v0
	v_mov_b32_e32 v12, v0
	v_mov_b32_e32 v13, v0
	v_mov_b32_e32 v14, v0
	v_mov_b32_e32 v15, v0
	v_add_f32_e32 v244, v0, v140
	v_cvt_pk_bf16_f32 v140, v56, v60
	v_cvt_pk_bf16_f32 v141, v57, v61
	v_cvt_pk_bf16_f32 v142, v130, v132
	v_cvt_pk_bf16_f32 v143, v131, v133
	v_mov_b32_e32 v17, v16
	v_mov_b32_e32 v18, v16
	v_mov_b32_e32 v19, v16
	v_mov_b32_e32 v20, v16
	v_mov_b32_e32 v21, v16
	v_mov_b32_e32 v22, v16
	v_mov_b32_e32 v23, v16
	v_mov_b32_e32 v24, v16
	v_mov_b32_e32 v25, v16
	v_mov_b32_e32 v26, v16
	v_mov_b32_e32 v27, v16
	v_mov_b32_e32 v28, v16
	v_mov_b32_e32 v29, v16
	v_mov_b32_e32 v30, v16
	v_mov_b32_e32 v31, v16
	v_cvt_pk_bf16_f32 v190, v36, v40
	v_cvt_pk_bf16_f32 v191, v37, v41
	v_cvt_pk_bf16_f32 v192, v46, v48
	v_cvt_pk_bf16_f32 v193, v47, v49
	v_cvt_pk_bf16_f32 v136, v134, v136
	v_cvt_pk_bf16_f32 v137, v135, v137
	v_cvt_pk_bf16_f32 v132, v54, v58
	v_cvt_pk_bf16_f32 v133, v55, v59
	v_cvt_pk_bf16_f32 v134, v128, v62
	v_cvt_pk_bf16_f32 v135, v129, v63
	v_cvt_pk_bf16_f32 v130, v150, v148
	v_cvt_pk_bf16_f32 v131, v151, v149
	v_cvt_pk_bf16_f32 v148, v34, v38
	v_cvt_pk_bf16_f32 v149, v35, v39
	v_cvt_pk_bf16_f32 v150, v44, v42
	v_cvt_pk_bf16_f32 v151, v45, v43
	s_waitcnt lgkmcnt(0)
	v_cvt_pk_bf16_f32 v138, v138, v152
	v_mfma_f32_32x32x16_bf16 v[32:47], v[92:95], v[140:143], v[0:15]
	v_cvt_pk_bf16_f32 v139, v139, v153
	v_cvt_pk_bf16_f32 v194, v158, v178
	v_cvt_pk_bf16_f32 v195, v159, v179
	v_cvt_pk_bf16_f32 v196, v184, v186
	v_cvt_pk_bf16_f32 v197, v185, v187
	v_cvt_pk_bf16_f32 v128, v146, v144
	v_cvt_pk_bf16_f32 v129, v147, v145
	v_mfma_f32_32x32x16_bf16 v[48:63], v[92:95], v[190:193], v[16:31]
	v_cvt_pk_bf16_f32 v144, v156, v154
	v_cvt_pk_bf16_f32 v145, v157, v155
	v_cvt_pk_bf16_f32 v146, v182, v180
	v_cvt_pk_bf16_f32 v147, v183, v181
	s_waitcnt vmcnt(2)
	s_barrier
	v_mfma_f32_32x32x16_bf16 v[0:15], v[88:91], v[140:143], v[0:15]
	v_ashrrev_i32_e32 v173, 31, v172
	s_mov_b32 s12, 0
	v_mfma_f32_32x32x16_bf16 v[16:31], v[88:91], v[190:193], v[16:31]
	v_mfma_f32_32x32x16_bf16 v[0:15], v[80:83], v[136:139], v[0:15]
	v_mfma_f32_32x32x16_bf16 v[16:31], v[80:83], v[194:197], v[16:31]
	v_mfma_f32_32x32x16_bf16 v[32:47], v[84:87], v[136:139], v[32:47]
	v_mfma_f32_32x32x16_bf16 v[48:63], v[84:87], v[194:197], v[48:63]
	v_mfma_f32_32x32x16_bf16 v[0:15], v[72:75], v[132:135], v[0:15]
	v_mfma_f32_32x32x16_bf16 v[16:31], v[72:75], v[148:151], v[16:31]
	v_mfma_f32_32x32x16_bf16 v[32:47], v[76:79], v[132:135], v[32:47]
	v_mfma_f32_32x32x16_bf16 v[48:63], v[76:79], v[148:151], v[48:63]
	v_mfma_f32_32x32x16_bf16 v[0:15], v[64:67], v[128:131], v[0:15]
	v_mfma_f32_32x32x16_bf16 v[16:31], v[64:67], v[144:147], v[16:31]
	v_add_u32_e32 v64, s5, v188
	v_mad_i64_i32 v[64:65], s[10:11], v64, s10, 0
	v_or_b32_e32 v64, v64, v189
	v_readlane_b32 s10, v255, 29
	v_lshl_add_u64 v[64:65], v[64:65], 0, v[160:161]
	v_readlane_b32 s11, v255, 30
	v_mfma_f32_32x32x16_bf16 v[32:47], v[68:71], v[128:131], v[32:47]
	v_and_b32_e32 v66, 7, v177
	v_lshl_add_u64 v[178:179], v[64:65], 1, s[10:11]
	v_add_u32_e32 v64, s5, v175
	s_movk_i32 s5, 0x600
	v_mad_i64_i32 v[64:65], s[10:11], v64, s5, 0
	v_readlane_b32 s10, v255, 31
	v_mfma_f32_32x32x16_bf16 v[48:63], v[68:71], v[144:147], v[48:63]
	v_lshl_or_b32 v64, v66, 4, v64
	v_readlane_b32 s11, v255, 32
	s_add_i32 s5, s19, -1
	s_nop 0
	v_lshl_add_u64 v[180:181], s[10:11], 0, v[64:65]
	s_getreg_b32 vcc_lo, hwreg(HW_REG_HW_ID, 0, 1)
	s_cmp_eq_u32 vcc_lo, 1
	s_cbranch_scc0 .Lprio_skip1
	s_setprio 1
.Lprio_skip1:
.LBB0_572:
	s_waitcnt lgkmcnt(0)
	v_mfma_f32_32x32x16_bf16 v[80:95], v[112:115], v[96:99], 0
	s_and_b64 vcc, exec, s[2:3]
	v_mfma_f32_32x32x16_bf16 v[64:79], v[116:119], v[96:99], 0
	v_mfma_f32_32x32x16_bf16 v[80:95], v[120:123], v[100:103], v[80:95]
	v_mfma_f32_32x32x16_bf16 v[64:79], v[124:127], v[100:103], v[64:79]
	s_cbranch_vccnz .Lda_anym0

.LBB0_645:
	v_readlane_b32 s10, v254, 33
	v_lshl_add_u64 v[14:15], v[114:115], 1, s[56:57]
	s_lshl_b32 s58, s10, 1
	v_lshl_add_u64 v[30:31], v[112:113], 1, s[74:75]
	v_lshl_add_u64 v[14:15], v[14:15], 0, s[58:59]
	s_add_i32 m0, s5, 0xf000
	v_lshl_add_u64 v[30:31], v[30:31], 0, s[58:59]
	global_load_lds_dwordx4 v[14:15], off
	s_add_i32 m0, s5, 0x12000
	v_add_f32_e32 v164, v0, v1
	global_load_lds_dwordx4 v[30:31], off
	v_cvt_pk_bf16_f32 v112, v116, v120
	v_cvt_pk_bf16_f32 v113, v117, v121
	v_cvt_pk_bf16_f32 v114, v18, v20
	v_cvt_pk_bf16_f32 v115, v19, v21
	v_cvt_pk_bf16_f32 v116, v16, v118
	v_cvt_pk_bf16_f32 v117, v17, v119
	v_cvt_pk_bf16_f32 v118, v4, v2
	v_cvt_pk_bf16_f32 v119, v5, v3
	v_cvt_pk_bf16_f32 v130, v8, v6
	v_cvt_pk_bf16_f32 v131, v9, v7
	v_cvt_pk_bf16_f32 v132, v12, v10
	v_cvt_pk_bf16_f32 v133, v13, v11
	v_mov_b32_e32 v1, v0
	v_mov_b32_e32 v2, v0
	v_mov_b32_e32 v3, v0
	v_mov_b32_e32 v4, v0
	v_mov_b32_e32 v5, v0
	v_mov_b32_e32 v6, v0
	v_mov_b32_e32 v7, v0
	v_mov_b32_e32 v8, v0
	v_mov_b32_e32 v9, v0
	v_mov_b32_e32 v10, v0
	v_mov_b32_e32 v11, v0
	v_mov_b32_e32 v12, v0
	v_mov_b32_e32 v13, v0
	v_mov_b32_e32 v14, v0
	v_mov_b32_e32 v15, v0
	v_cvt_pk_bf16_f32 v126, v22, v24
	v_cvt_pk_bf16_f32 v127, v23, v25
	v_cvt_pk_bf16_f32 v128, v26, v28
	v_cvt_pk_bf16_f32 v129, v27, v29
	s_waitcnt lgkmcnt(0)
	v_readlane_b32 s10, v255, 33
	v_mfma_f32_32x32x16_bf16 v[16:31], v[60:63], v[112:115], v[0:15]
	v_readlane_b32 s11, v255, 34
	s_waitcnt vmcnt(2)
	s_barrier
	v_mfma_f32_32x32x16_bf16 v[0:15], v[32:35], v[112:115], v[0:15]
	v_add_u32_e32 v32, s7, v123
	v_ashrrev_i32_e32 v33, 31, v32
	v_lshlrev_b64 v[32:33], 10, v[32:33]
	v_and_b32_e32 v34, 7, v125
	v_lshl_or_b32 v32, v34, 4, v32
	v_lshl_add_u64 v[148:149], s[10:11], 0, v[32:33]
	v_add_u32_e32 v32, s7, v124
	v_mfma_f32_32x32x16_bf16 v[16:31], v[56:59], v[126:129], v[16:31]
	v_ashrrev_i32_e32 v33, 31, v32
	v_lshlrev_b64 v[32:33], 9, v[32:33]
	v_or_b32_e32 v32, v32, v122
	v_readlane_b32 s10, v255, 35
	v_lshl_add_u64 v[32:33], v[32:33], 0, v[160:161]
	v_readlane_b32 s11, v255, 36
	s_mov_b32 s7, 2
	v_mfma_f32_32x32x16_bf16 v[0:15], v[36:39], v[126:129], v[0:15]
	v_lshl_add_u64 v[150:151], v[32:33], 1, s[10:11]
	v_mfma_f32_32x32x16_bf16 v[16:31], v[52:55], v[116:119], v[16:31]
	v_mfma_f32_32x32x16_bf16 v[0:15], v[40:43], v[116:119], v[0:15]
	v_mfma_f32_32x32x16_bf16 v[16:31], v[48:51], v[130:133], v[16:31]
	v_mfma_f32_32x32x16_bf16 v[0:15], v[44:47], v[130:133], v[0:15]
	s_getreg_b32 vcc_lo, hwreg(HW_REG_HW_ID, 0, 1)
	s_cmp_eq_u32 vcc_lo, 1
	s_cbranch_scc0 .Lprio_skip2
	s_setprio 1
.Lprio_skip2:
	s_branch .LBB0_647

.LBB0_678:
	v_add_f32_e32 v185, v32, v142
	v_add_u32_e32 v32, s16, v139
	v_ashrrev_i32_e32 v33, 31, v32
	v_lshlrev_b64 v[32:33], 9, v[32:33]
	v_or_b32_e32 v32, v32, v138
	v_readlane_b32 s14, v255, 23
	v_lshl_add_u64 v[32:33], v[32:33], 0, v[160:161]
	v_readlane_b32 s15, v255, 24
	s_lshl_b32 s7, s7, 7
	s_and_b32 s7, s7, 0x6000
	v_lshl_add_u64 v[156:157], v[32:33], 1, s[14:15]
	v_lshlrev_b32_e32 v32, 9, v140
	v_or3_b32 v32, s7, v32, v141
	v_readlane_b32 s14, v255, 25
	v_lshlrev_b32_e32 v32, 1, v32
	v_mov_b32_e32 v33, v161
	v_readlane_b32 s15, v255, 26
	s_barrier
	v_and_b32_e32 v34, 7, v136
	v_lshl_add_u64 v[158:159], s[14:15], 0, v[32:33]
	v_add_u32_e32 v32, s16, v137
	v_ashrrev_i32_e32 v33, 31, v32
	v_lshlrev_b64 v[32:33], 10, v[32:33]
	v_readlane_b32 s14, v255, 27
	v_lshl_or_b32 v32, v34, 4, v32
	v_readlane_b32 s15, v255, 28
	s_mov_b32 s7, 4
	s_sub_i32 s21, 2, s19
	v_lshl_add_u64 v[172:173], s[14:15], 0, v[32:33]
	s_getreg_b32 s14, hwreg(HW_REG_HW_ID, 0, 1)
	s_cmp_eq_u32 s14, 1
	s_cbranch_scc0 .Lprio_skip3
	s_setprio 1
